# main G1 peeled first K iteration: its first two counted waits no longer drain the previous tile's 16 output stores (vmcnt 18 / 24 instead of 8)
# baseline (speedup 1.0000x reference)
.LBB0_56:
	s_ashr_i32 s95, s94, 31
	s_lshl_b64 s[6:7], s[94:95], 19
	v_readlane_b32 s9, v253, 5
	s_add_u32 s80, s9, s6
	v_readlane_b32 s6, v253, 6
	s_addc_u32 s81, s6, s7
	s_and_b64 s[6:7], s[42:43], exec
	s_cselect_b32 s9, s81, s1
	s_cselect_b32 s11, s80, s0
	s_ashr_i32 s93, s92, 31
	s_lshl_b64 s[6:7], s[92:93], 19
	v_readlane_b32 s12, v253, 61
	s_add_u32 s82, s12, s6
	v_readlane_b32 s6, v253, 62
	s_addc_u32 s83, s6, s7
	s_and_b64 s[6:7], s[42:43], exec
	s_cselect_b32 s12, s83, s5
	s_cselect_b32 s13, s82, s4
	s_add_u32 s0, s0, 0x40080
	s_addc_u32 s1, s1, 0
	s_add_u32 s14, s4, 0x100
	s_addc_u32 s15, s5, 0
	s_mov_b32 s16, -2
	s_add_u32 s4, s0, 0xfffc0080
	s_addc_u32 s5, s1, -1
	s_add_i32 s17, 0, 0x10000
	s_cmp_eq_u32 s16, 12
	s_cselect_b32 s7, s9, s5
	s_cselect_b32 s6, s11, s4
	v_add_u32_e32 v0, s17, v198
	s_cselect_b32 s5, s12, s15
	s_cselect_b32 s4, s13, s14
	s_add_i32 s20, 0, 0x14000
	ds_read_b128 v[18:21], v0
	ds_read_b128 v[22:25], v0 offset:1024
	ds_read_b128 v[34:37], v0 offset:2048
	ds_read_b128 v[38:41], v0 offset:3072
	v_add_u32_e32 v0, s20, v198
	ds_read_b128 v[146:149], v0
	ds_read_b128 v[150:153], v0 offset:1024
	ds_read_b128 v[172:175], v0 offset:2048
	ds_read_b128 v[176:179], v0 offset:3072
	s_add_i32 m0, s69, 0xc000
	ds_read_b128 v[180:183], v200
	ds_read_b128 v[184:187], v200 offset:1024
	ds_read_b128 v[202:205], v200 offset:2048
	ds_read_b128 v[206:209], v200 offset:3072
	ds_read_b128 v[210:213], v200 offset:4096
	ds_read_b128 v[214:217], v200 offset:5120
	ds_read_b128 v[218:221], v200 offset:6144
	ds_read_b128 v[234:237], v200 offset:7168
	global_load_lds_dwordx4 v168, s[0:1]
	s_add_i32 m0, s69, 0xe000
	s_nop 0
	global_load_lds_dwordx4 v170, s[0:1]
	s_waitcnt vmcnt(18)
	s_waitcnt lgkmcnt(0)
	s_barrier
	s_setprio 1
	s_waitcnt lgkmcnt(0)
	v_mfma_f32_16x16x32_bf16 v[142:145], v[18:21], v[180:183], 0
	v_mfma_f32_16x16x32_bf16 v[138:141], v[34:37], v[180:183], 0
	v_mfma_f32_16x16x32_bf16 v[126:129], v[18:21], v[202:205], 0
	v_mfma_f32_16x16x32_bf16 v[122:125], v[34:37], v[202:205], 0
	v_mfma_f32_16x16x32_bf16 v[110:113], v[18:21], v[210:213], 0
	v_mfma_f32_16x16x32_bf16 v[106:109], v[34:37], v[210:213], 0
	v_mfma_f32_16x16x32_bf16 v[94:97], v[18:21], v[218:221], 0
	v_mfma_f32_16x16x32_bf16 v[90:93], v[34:37], v[218:221], 0
	v_mfma_f32_16x16x32_bf16 v[142:145], v[22:25], v[184:187], v[142:145]
	v_mfma_f32_16x16x32_bf16 v[138:141], v[38:41], v[184:187], v[138:141]
	v_mfma_f32_16x16x32_bf16 v[126:129], v[22:25], v[206:209], v[126:129]
	v_mfma_f32_16x16x32_bf16 v[122:125], v[38:41], v[206:209], v[122:125]
	v_mfma_f32_16x16x32_bf16 v[110:113], v[22:25], v[214:217], v[110:113]
	v_mfma_f32_16x16x32_bf16 v[106:109], v[38:41], v[214:217], v[106:109]
	v_mfma_f32_16x16x32_bf16 v[94:97], v[22:25], v[234:237], v[94:97]
	v_mfma_f32_16x16x32_bf16 v[90:93], v[38:41], v[234:237], v[90:93]
	s_setprio 0
	s_setprio 1
	v_mfma_f32_16x16x32_bf16 v[134:137], v[146:149], v[180:183], 0
	v_mfma_f32_16x16x32_bf16 v[130:133], v[172:175], v[180:183], 0
	v_mfma_f32_16x16x32_bf16 v[118:121], v[146:149], v[202:205], 0
	v_mfma_f32_16x16x32_bf16 v[114:117], v[172:175], v[202:205], 0
	v_mfma_f32_16x16x32_bf16 v[102:105], v[146:149], v[210:213], 0
	v_mfma_f32_16x16x32_bf16 v[98:101], v[172:175], v[210:213], 0
	v_mfma_f32_16x16x32_bf16 v[86:89], v[146:149], v[218:221], 0
	v_mfma_f32_16x16x32_bf16 v[82:85], v[172:175], v[218:221], 0
	v_mfma_f32_16x16x32_bf16 v[134:137], v[150:153], v[184:187], v[134:137]
	v_mfma_f32_16x16x32_bf16 v[130:133], v[176:179], v[184:187], v[130:133]
	v_mfma_f32_16x16x32_bf16 v[118:121], v[150:153], v[206:209], v[118:121]
	v_mfma_f32_16x16x32_bf16 v[114:117], v[176:179], v[206:209], v[114:117]
	v_mfma_f32_16x16x32_bf16 v[102:105], v[150:153], v[214:217], v[102:105]
	v_mfma_f32_16x16x32_bf16 v[98:101], v[176:179], v[214:217], v[98:101]
	v_mfma_f32_16x16x32_bf16 v[86:89], v[150:153], v[234:237], v[86:89]
	v_mfma_f32_16x16x32_bf16 v[82:85], v[176:179], v[234:237], v[82:85]
	s_setprio 0
	s_barrier
	s_add_i32 s17, s17, s87
	s_mov_b32 m0, s17
	ds_read_b128 v[180:183], v200 offset:16384
	ds_read_b128 v[184:187], v200 offset:17408
	ds_read_b128 v[202:205], v200 offset:18432
	ds_read_b128 v[206:209], v200 offset:19456
	ds_read_b128 v[210:213], v200 offset:20480
	ds_read_b128 v[214:217], v200 offset:21504
	ds_read_b128 v[218:221], v200 offset:22528
	ds_read_b128 v[234:237], v200 offset:23552
	global_load_lds_dwordx4 v158, s[4:5]
	s_add_i32 m0, s17, 0x2000
	s_add_u32 s98, s6, s48
	s_addc_u32 s99, s7, s49
	s_add_u32 s18, s4, 0x40000
	s_addc_u32 s19, s5, 0
	s_add_i32 s17, s20, s87
	global_load_lds_dwordx4 v154, s[4:5]
	s_mov_b32 m0, s17
	s_nop 0
	global_load_lds_dwordx4 v158, s[18:19]
	s_add_i32 m0, s17, 0x2000
	s_nop 0
	global_load_lds_dwordx4 v154, s[18:19]
	s_mov_b32 m0, s69
	s_nop 0
	global_load_lds_dwordx4 v160, s[6:7]
	s_mov_b32 m0, s76
	s_nop 0
	global_load_lds_dwordx4 v156, s[6:7]
	s_waitcnt vmcnt(24)
	s_waitcnt lgkmcnt(0)
	s_barrier
	s_setprio 1
	s_waitcnt lgkmcnt(0)
	v_mfma_f32_16x16x32_bf16 v[78:81], v[18:21], v[180:183], 0
	v_mfma_f32_16x16x32_bf16 v[74:77], v[34:37], v[180:183], 0
	v_mfma_f32_16x16x32_bf16 v[62:65], v[18:21], v[202:205], 0
	v_mfma_f32_16x16x32_bf16 v[58:61], v[34:37], v[202:205], 0
	v_mfma_f32_16x16x32_bf16 v[46:49], v[18:21], v[210:213], 0
	v_mfma_f32_16x16x32_bf16 v[42:45], v[34:37], v[210:213], 0
	v_mfma_f32_16x16x32_bf16 v[14:17], v[18:21], v[218:221], 0
	v_mfma_f32_16x16x32_bf16 v[10:13], v[34:37], v[218:221], 0
	v_mfma_f32_16x16x32_bf16 v[78:81], v[22:25], v[184:187], v[78:81]
	v_mfma_f32_16x16x32_bf16 v[74:77], v[38:41], v[184:187], v[74:77]
	v_mfma_f32_16x16x32_bf16 v[62:65], v[22:25], v[206:209], v[62:65]
	v_mfma_f32_16x16x32_bf16 v[58:61], v[38:41], v[206:209], v[58:61]
	v_mfma_f32_16x16x32_bf16 v[46:49], v[22:25], v[214:217], v[46:49]
	v_mfma_f32_16x16x32_bf16 v[42:45], v[38:41], v[214:217], v[42:45]
	v_mfma_f32_16x16x32_bf16 v[14:17], v[22:25], v[234:237], v[14:17]
	v_mfma_f32_16x16x32_bf16 v[10:13], v[38:41], v[234:237], v[10:13]
	s_setprio 0
	s_setprio 1
	v_mfma_f32_16x16x32_bf16 v[30:33], v[146:149], v[210:213], 0
	v_mfma_f32_16x16x32_bf16 v[26:29], v[172:175], v[210:213], 0
	v_mfma_f32_16x16x32_bf16 v[6:9], v[146:149], v[218:221], 0
	v_mfma_f32_16x16x32_bf16 v[2:5], v[172:175], v[218:221], 0
	v_mfma_f32_16x16x32_bf16 v[18:21], v[146:149], v[180:183], 0
	v_mfma_f32_16x16x32_bf16 v[22:25], v[172:175], v[180:183], 0
	v_mfma_f32_16x16x32_bf16 v[34:37], v[146:149], v[202:205], 0
	v_mfma_f32_16x16x32_bf16 v[38:41], v[172:175], v[202:205], 0
	v_mfma_f32_16x16x32_bf16 v[30:33], v[150:153], v[214:217], v[30:33]
	v_mfma_f32_16x16x32_bf16 v[26:29], v[176:179], v[214:217], v[26:29]
	v_mfma_f32_16x16x32_bf16 v[6:9], v[150:153], v[234:237], v[6:9]
	v_mfma_f32_16x16x32_bf16 v[2:5], v[176:179], v[234:237], v[2:5]
	v_mfma_f32_16x16x32_bf16 v[18:21], v[150:153], v[184:187], v[18:21]
	v_mfma_f32_16x16x32_bf16 v[22:25], v[176:179], v[184:187], v[22:25]
	v_mfma_f32_16x16x32_bf16 v[34:37], v[150:153], v[206:209], v[34:37]
	v_mfma_f32_16x16x32_bf16 v[38:41], v[176:179], v[206:209], v[38:41]
	s_setprio 0
	s_barrier
	s_add_i32 s17, 0, 0x18000
	v_add_u32_e32 v0, s17, v198
	s_add_i32 s18, 0, 0x1c000
	ds_read_b128 v[50:53], v0
	ds_read_b128 v[54:57], v0 offset:1024
	ds_read_b128 v[66:69], v0 offset:2048
	ds_read_b128 v[70:73], v0 offset:3072
	v_add_u32_e32 v0, s18, v198
	ds_read_b128 v[146:149], v0
	ds_read_b128 v[150:153], v0 offset:1024
	ds_read_b128 v[172:175], v0 offset:2048
	ds_read_b128 v[176:179], v0 offset:3072
	s_add_u32 s6, s6, 0x40000
	s_addc_u32 s7, s7, 0
	s_mov_b32 m0, s77
	ds_read_b128 v[180:183], v200 offset:32768
	ds_read_b128 v[184:187], v200 offset:33792
	ds_read_b128 v[202:205], v200 offset:34816
	ds_read_b128 v[206:209], v200 offset:35840
	ds_read_b128 v[210:213], v200 offset:36864
	ds_read_b128 v[214:217], v200 offset:37888
	ds_read_b128 v[218:221], v200 offset:38912
	ds_read_b128 v[234:237], v200 offset:39936
	global_load_lds_dwordx4 v160, s[6:7]
	s_mov_b32 m0, s96
	s_nop 0
	global_load_lds_dwordx4 v156, s[6:7]
	s_waitcnt vmcnt(8)
	s_waitcnt lgkmcnt(0)
	s_barrier
	s_setprio 1
	s_waitcnt lgkmcnt(0)
	v_mfma_f32_16x16x32_bf16 v[142:145], v[50:53], v[180:183], v[142:145]
	v_mfma_f32_16x16x32_bf16 v[138:141], v[66:69], v[180:183], v[138:141]
	v_mfma_f32_16x16x32_bf16 v[126:129], v[50:53], v[202:205], v[126:129]
	v_mfma_f32_16x16x32_bf16 v[122:125], v[66:69], v[202:205], v[122:125]
	v_mfma_f32_16x16x32_bf16 v[110:113], v[50:53], v[210:213], v[110:113]
	v_mfma_f32_16x16x32_bf16 v[106:109], v[66:69], v[210:213], v[106:109]
	v_mfma_f32_16x16x32_bf16 v[94:97], v[50:53], v[218:221], v[94:97]
	v_mfma_f32_16x16x32_bf16 v[90:93], v[66:69], v[218:221], v[90:93]
	v_mfma_f32_16x16x32_bf16 v[142:145], v[54:57], v[184:187], v[142:145]
	v_mfma_f32_16x16x32_bf16 v[138:141], v[70:73], v[184:187], v[138:141]
	v_mfma_f32_16x16x32_bf16 v[126:129], v[54:57], v[206:209], v[126:129]
	v_mfma_f32_16x16x32_bf16 v[122:125], v[70:73], v[206:209], v[122:125]
	v_mfma_f32_16x16x32_bf16 v[110:113], v[54:57], v[214:217], v[110:113]
	v_mfma_f32_16x16x32_bf16 v[106:109], v[70:73], v[214:217], v[106:109]
	v_mfma_f32_16x16x32_bf16 v[94:97], v[54:57], v[234:237], v[94:97]
	v_mfma_f32_16x16x32_bf16 v[90:93], v[70:73], v[234:237], v[90:93]
	s_setprio 0
	s_setprio 1
	v_mfma_f32_16x16x32_bf16 v[134:137], v[146:149], v[180:183], v[134:137]
	v_mfma_f32_16x16x32_bf16 v[130:133], v[172:175], v[180:183], v[130:133]
	v_mfma_f32_16x16x32_bf16 v[118:121], v[146:149], v[202:205], v[118:121]
	v_mfma_f32_16x16x32_bf16 v[114:117], v[172:175], v[202:205], v[114:117]
	v_mfma_f32_16x16x32_bf16 v[102:105], v[146:149], v[210:213], v[102:105]
	v_mfma_f32_16x16x32_bf16 v[98:101], v[172:175], v[210:213], v[98:101]
	v_mfma_f32_16x16x32_bf16 v[86:89], v[146:149], v[218:221], v[86:89]
	v_mfma_f32_16x16x32_bf16 v[82:85], v[172:175], v[218:221], v[82:85]
	v_mfma_f32_16x16x32_bf16 v[134:137], v[150:153], v[184:187], v[134:137]
	v_mfma_f32_16x16x32_bf16 v[130:133], v[176:179], v[184:187], v[130:133]
	v_mfma_f32_16x16x32_bf16 v[118:121], v[150:153], v[206:209], v[118:121]
	v_mfma_f32_16x16x32_bf16 v[114:117], v[176:179], v[206:209], v[114:117]
	v_mfma_f32_16x16x32_bf16 v[102:105], v[150:153], v[214:217], v[102:105]
	v_mfma_f32_16x16x32_bf16 v[98:101], v[176:179], v[214:217], v[98:101]
	v_mfma_f32_16x16x32_bf16 v[86:89], v[150:153], v[234:237], v[86:89]
	v_mfma_f32_16x16x32_bf16 v[82:85], v[176:179], v[234:237], v[82:85]
	s_setprio 0
	s_barrier
	s_add_i32 s6, s17, s87
	s_add_u32 vcc_lo, s4, s48
	s_addc_u32 vcc_hi, s5, s49
	s_mov_b32 m0, s6
	ds_read_b128 v[180:183], v200 offset:49152
	ds_read_b128 v[184:187], v200 offset:50176
	ds_read_b128 v[202:205], v200 offset:51200
	ds_read_b128 v[206:209], v200 offset:52224
	ds_read_b128 v[210:213], v200 offset:53248
	ds_read_b128 v[214:217], v200 offset:54272
	ds_read_b128 v[218:221], v200 offset:55296
	ds_read_b128 v[234:237], v200 offset:56320
	global_load_lds_dwordx4 v158, vcc
	s_add_i32 m0, s6, 0x2000
	s_add_u32 s4, s4, 0x40080
	s_addc_u32 s5, s5, 0
	s_add_i32 s6, s18, s87
	global_load_lds_dwordx4 v154, vcc
	s_mov_b32 m0, s6
	s_nop 0
	global_load_lds_dwordx4 v158, s[4:5]
	s_add_i32 m0, s6, 0x2000
	s_nop 0
	global_load_lds_dwordx4 v154, s[4:5]
	s_mov_b32 m0, s74
	s_nop 0
	global_load_lds_dwordx4 v160, s[98:99]
	s_mov_b32 m0, s75
	s_nop 0
	global_load_lds_dwordx4 v156, s[98:99]
	s_waitcnt vmcnt(8)
	s_waitcnt lgkmcnt(0)
	s_barrier
	s_setprio 1
	s_waitcnt lgkmcnt(0)
	v_mfma_f32_16x16x32_bf16 v[78:81], v[50:53], v[180:183], v[78:81]
	v_mfma_f32_16x16x32_bf16 v[74:77], v[66:69], v[180:183], v[74:77]
	v_mfma_f32_16x16x32_bf16 v[62:65], v[50:53], v[202:205], v[62:65]
	v_mfma_f32_16x16x32_bf16 v[58:61], v[66:69], v[202:205], v[58:61]
	v_mfma_f32_16x16x32_bf16 v[46:49], v[50:53], v[210:213], v[46:49]
	v_mfma_f32_16x16x32_bf16 v[42:45], v[66:69], v[210:213], v[42:45]
	v_mfma_f32_16x16x32_bf16 v[14:17], v[50:53], v[218:221], v[14:17]
	v_mfma_f32_16x16x32_bf16 v[10:13], v[66:69], v[218:221], v[10:13]
	v_mfma_f32_16x16x32_bf16 v[78:81], v[54:57], v[184:187], v[78:81]
	v_mfma_f32_16x16x32_bf16 v[74:77], v[70:73], v[184:187], v[74:77]
	v_mfma_f32_16x16x32_bf16 v[62:65], v[54:57], v[206:209], v[62:65]
	v_mfma_f32_16x16x32_bf16 v[58:61], v[70:73], v[206:209], v[58:61]
	v_mfma_f32_16x16x32_bf16 v[46:49], v[54:57], v[214:217], v[46:49]
	v_mfma_f32_16x16x32_bf16 v[42:45], v[70:73], v[214:217], v[42:45]
	v_mfma_f32_16x16x32_bf16 v[14:17], v[54:57], v[234:237], v[14:17]
	v_mfma_f32_16x16x32_bf16 v[10:13], v[70:73], v[234:237], v[10:13]
	s_setprio 0
	s_setprio 1
	v_mfma_f32_16x16x32_bf16 v[18:21], v[146:149], v[180:183], v[18:21]
	v_mfma_f32_16x16x32_bf16 v[70:73], v[150:153], v[184:187], v[18:21]
	v_mfma_f32_16x16x32_bf16 v[18:21], v[172:175], v[180:183], v[22:25]
	v_mfma_f32_16x16x32_bf16 v[66:69], v[176:179], v[184:187], v[18:21]
	v_mfma_f32_16x16x32_bf16 v[18:21], v[146:149], v[202:205], v[34:37]
	v_mfma_f32_16x16x32_bf16 v[54:57], v[150:153], v[206:209], v[18:21]
	v_mfma_f32_16x16x32_bf16 v[18:21], v[172:175], v[202:205], v[38:41]
	v_mfma_f32_16x16x32_bf16 v[50:53], v[176:179], v[206:209], v[18:21]
	v_mfma_f32_16x16x32_bf16 v[18:21], v[146:149], v[210:213], v[30:33]
	v_mfma_f32_16x16x32_bf16 v[30:33], v[150:153], v[214:217], v[18:21]
	v_mfma_f32_16x16x32_bf16 v[18:21], v[172:175], v[210:213], v[26:29]
	v_mfma_f32_16x16x32_bf16 v[6:9], v[146:149], v[218:221], v[6:9]
	v_mfma_f32_16x16x32_bf16 v[2:5], v[172:175], v[218:221], v[2:5]
	v_mfma_f32_16x16x32_bf16 v[26:29], v[176:179], v[214:217], v[18:21]
	v_mfma_f32_16x16x32_bf16 v[6:9], v[150:153], v[234:237], v[6:9]
	v_mfma_f32_16x16x32_bf16 v[2:5], v[176:179], v[234:237], v[2:5]
	s_setprio 0
	s_barrier
	s_add_i32 s16, s16, 2
	s_add_u32 s0, s0, 0x100
	s_addc_u32 s1, s1, 0
	s_add_u32 s14, s14, 0x100
	s_addc_u32 s15, s15, 0
	s_cmp_gt_u32 s16, 13
	s_cbranch_scc0 .LBB0_57
